# v25 + MLA QK cluster: one lgkmcnt(0) for the K fragments instead of 11 counted waits; empty setprio pair removed
# baseline (speedup 1.0000x reference)
; #define MFMA(a, b, c) __builtin_amdgcn_mfma_f32_32x32x16_bf16((a), (b), (c), 0, 0, 0)
; template <int DK, int MODE> ...
;     ...
;     if (active) {
;       f32x16 s0, s1;
;       const bf16_t* kb = sK + cur * 64 * LDK + l32 * LDK + h * 8;
;       bf16x8 kf0[NKS], kf1[NKS];
; #pragma unroll
;       for (int ks = 0; ks < NKS; ++ks) { kf0[ks] = *(const bf16x8*)(kb + ks * 16); kf1[ks] = *(const bf16x8*)(kb + 32 * LDK + ks * 16); }
;       if (MODE == 1) {
;         const float* fb = sF + cur * 64 + 4 * h;
; #pragma unroll
;         for (int g = 0; g < 4; ++g) {
;           const f32x4 f0 = *(const f32x4*)(fb + 8 * g), f1 = *(const f32x4*)(fb + 32 + 8 * g);
;           s0[4 * g] = f0.x; s0[4 * g + 1] = f0.y; s0[4 * g + 2] = f0.z; s0[4 * g + 3] = f0.w;
;           s1[4 * g] = f1.x; s1[4 * g + 1] = f1.y; s1[4 * g + 2] = f1.z; s1[4 * g + 3] = f1.w;
;         }
;       } else {
; #pragma unroll
;         for (int e = 0; e < 16; ++e) { s0[e] = 0.f; s1[e] = 0.f; }
;       }
;       __builtin_amdgcn_iglp_opt(0);
;       __builtin_amdgcn_s_setprio(1);
; #pragma unroll
;       for (int ks = 0; ks < NKS; ++ks) { s0 = MFMA(kf0[ks], qf[ks], s0); s1 = MFMA(kf1[ks], qf[ks], s1); }
;       __builtin_amdgcn_s_setprio(0);
;       const bf16_t* vb = sV + cur * 64 * 72 + l32 * 72 + h * 8;
;       bf16x8 vf0[4], vf1[4];
; #pragma unroll
;       for (int j = 0; j < 4; ++j) { vf0[j] = *(const bf16x8*)(vb + j * 16); vf1[j] = *(const bf16x8*)(vb + 32 * 72 + j * 16); }
;       __builtin_amdgcn_sched_barrier(0);
;       const bool need_mask = CAUSAL && (key0 + 63 >= tq0);
;       bf16x8 pf[4];
;       if (MODE != 2) {
;         if (need_mask) {
; #pragma unroll
;           for (int e = 0; e < 16; ++e) {
;             const int key = key0 + 8 * (e >> 2) + 4 * h + (e & 3);
;             if (key > qpos) s0[e] = -1e30f;
;             if (key + 32 > qpos) s1[e] = -1e30f;
;           }
.LBB0_526:
	s_and_b32 s11, s10, 1
	s_cmp_gt_i32 s9, s8
	s_cbranch_scc1 .Lmla_inactive
	s_mul_i32 s12, s11, 0x3400
	v_add_u32_e32 v0, s12, v175
	ds_read_b128 v[48:51], v0 offset:6656
	ds_read_b128 v[52:55], v0
	ds_read_b128 v[92:95], v0 offset:32
	ds_read_b128 v[96:99], v0 offset:6688
	ds_read_b128 v[100:103], v0 offset:64
	ds_read_b128 v[104:107], v0 offset:6720
	ds_read_b128 v[108:111], v0 offset:96
	ds_read_b128 v[132:135], v0 offset:6752
	ds_read_b128 v[136:139], v0 offset:128
	ds_read_b128 v[140:143], v0 offset:6784
	ds_read_b128 v[176:179], v0 offset:160
	ds_read_b128 v[180:183], v0 offset:6816
	s_waitcnt lgkmcnt(0)
	v_mfma_f32_32x32x16_bf16 v[64:79], v[52:55], v[80:83], 0
	s_mul_i32 s12, s11, 0x2400
	v_add_u32_e32 v0, s12, v157
	v_mfma_f32_32x32x16_bf16 v[48:63], v[48:51], v[80:83], 0
	v_lshl_add_u64 v[2:3], v[170:171], 0, s[46:47]
	global_load_dwordx4 v[88:91], v[2:3], off
	v_mfma_f32_32x32x16_bf16 v[64:79], v[92:95], v[128:131], v[64:79]
	ds_read_b128 v[92:95], v0 offset:31328
	v_mfma_f32_32x32x16_bf16 v[48:63], v[96:99], v[128:131], v[48:63]
	v_lshl_add_u64 v[2:3], v[168:169], 0, s[46:47]
	global_load_dwordx4 v[84:87], v[2:3], off
	ds_read_b128 v[96:99], v0 offset:26720
	v_mfma_f32_32x32x16_bf16 v[64:79], v[100:103], v[124:127], v[64:79]
	ds_read_b128 v[100:103], v0 offset:26688
	v_mfma_f32_32x32x16_bf16 v[48:63], v[104:107], v[124:127], v[48:63]
	v_lshl_add_u64 v[2:3], v[166:167], 0, s[46:47]
	global_load_dwordx4 v[10:13], v[2:3], off
	ds_read_b128 v[104:107], v0 offset:31296
	v_mfma_f32_32x32x16_bf16 v[64:79], v[108:111], v[120:123], v[64:79]
	ds_read_b128 v[108:111], v0 offset:26656
	v_mfma_f32_32x32x16_bf16 v[48:63], v[132:135], v[120:123], v[48:63]
	global_load_dwordx4 v[6:9], v[164:165], off
	ds_read_b128 v[132:135], v0 offset:31264
	v_mfma_f32_32x32x16_bf16 v[64:79], v[136:139], v[116:119], v[64:79]
	ds_read_b128 v[136:139], v0 offset:26624
	v_mfma_f32_32x32x16_bf16 v[48:63], v[140:143], v[116:119], v[48:63]
	s_nop 0
	global_load_dwordx4 v[2:5], v[162:163], off
	ds_read_b128 v[140:143], v0 offset:31232
	v_mfma_f32_32x32x16_bf16 v[64:79], v[176:179], v[112:115], v[64:79]
	v_mfma_f32_32x32x16_bf16 v[48:63], v[180:183], v[112:115], v[48:63]
	s_add_i32 s12, s9, 63
	s_cmp_lt_i32 s12, s1
	s_cbranch_scc1 .LBB0_529
	v_add_u32_e32 v0, s9, v149
	v_add_u32_e32 v14, 32, v0
	v_cmp_le_i32_e32 vcc, v14, v152
	v_add_u32_e32 v14, 33, v0
	s_nop 4
	v_cndmask_b32_e32 v48, v198, v48, vcc
	v_cmp_lt_i32_e32 vcc, v0, v152
	s_nop 1
	v_cndmask_b32_e32 v65, v198, v65, vcc
	v_cmp_le_i32_e32 vcc, v0, v152
	s_nop 1
	v_cndmask_b32_e32 v64, v198, v64, vcc
	v_cmp_le_i32_e32 vcc, v14, v152
	v_add_u32_e32 v14, 2, v0
	s_nop 0
	v_cndmask_b32_e32 v49, v198, v49, vcc
	v_cmp_le_i32_e32 vcc, v14, v152
	v_add_u32_e32 v14, 34, v0
	s_nop 0
	v_cndmask_b32_e32 v66, v198, v66, vcc
	v_cmp_le_i32_e32 vcc, v14, v152
	v_add_u32_e32 v14, 3, v0
	s_nop 0
	v_cndmask_b32_e32 v50, v198, v50, vcc
	v_cmp_le_i32_e32 vcc, v14, v152
	v_add_u32_e32 v14, 35, v0
	s_nop 0
	v_cndmask_b32_e32 v67, v198, v67, vcc
	v_cmp_le_i32_e32 vcc, v14, v152
	v_add_u32_e32 v14, 8, v0
	s_nop 0
	v_cndmask_b32_e32 v51, v198, v51, vcc
	v_cmp_le_i32_e32 vcc, v14, v152
	v_add_u32_e32 v14, 40, v0
	s_nop 0
	v_cndmask_b32_e32 v68, v198, v68, vcc
	v_cmp_le_i32_e32 vcc, v14, v152
	v_add_u32_e32 v14, 9, v0
	s_nop 0
	v_cndmask_b32_e32 v52, v198, v52, vcc
	v_cmp_le_i32_e32 vcc, v14, v152
	v_add_u32_e32 v14, 41, v0
	s_nop 0
	v_cndmask_b32_e32 v69, v198, v69, vcc
	v_cmp_le_i32_e32 vcc, v14, v152
	v_add_u32_e32 v14, 10, v0
	s_nop 0
	v_cndmask_b32_e32 v53, v198, v53, vcc
	v_cmp_le_i32_e32 vcc, v14, v152
	v_add_u32_e32 v14, 42, v0
	s_nop 0
	v_cndmask_b32_e32 v70, v198, v70, vcc
	v_cmp_le_i32_e32 vcc, v14, v152
	v_add_u32_e32 v14, 11, v0
	s_nop 0
	v_cndmask_b32_e32 v54, v198, v54, vcc
	v_cmp_le_i32_e32 vcc, v14, v152
	v_add_u32_e32 v14, 43, v0
	s_nop 0
	v_cndmask_b32_e32 v71, v198, v71, vcc
	v_cmp_le_i32_e32 vcc, v14, v152
	v_add_u32_e32 v14, 16, v0
	s_nop 0
	v_cndmask_b32_e32 v55, v198, v55, vcc
	v_cmp_le_i32_e32 vcc, v14, v152
	v_add_u32_e32 v14, 48, v0
	s_nop 0
	v_cndmask_b32_e32 v72, v198, v72, vcc
	v_cmp_le_i32_e32 vcc, v14, v152
	v_add_u32_e32 v14, 17, v0
	s_nop 0
	v_cndmask_b32_e32 v56, v198, v56, vcc
	v_cmp_le_i32_e32 vcc, v14, v152
	v_add_u32_e32 v14, 49, v0
	s_nop 0
	v_cndmask_b32_e32 v73, v198, v73, vcc
	v_cmp_le_i32_e32 vcc, v14, v152
	v_add_u32_e32 v14, 18, v0
	s_nop 0
	v_cndmask_b32_e32 v57, v198, v57, vcc
	v_cmp_le_i32_e32 vcc, v14, v152
	v_add_u32_e32 v14, 50, v0
	s_nop 0
	v_cndmask_b32_e32 v74, v198, v74, vcc
	v_cmp_le_i32_e32 vcc, v14, v152
	v_add_u32_e32 v14, 19, v0
	s_nop 0
	v_cndmask_b32_e32 v58, v198, v58, vcc
	v_cmp_le_i32_e32 vcc, v14, v152
	v_add_u32_e32 v14, 51, v0
	s_nop 0
	v_cndmask_b32_e32 v75, v198, v75, vcc
	v_cmp_le_i32_e32 vcc, v14, v152
	v_add_u32_e32 v14, 24, v0
	s_nop 0
	v_cndmask_b32_e32 v59, v198, v59, vcc
	v_cmp_le_i32_e32 vcc, v14, v152
	v_add_u32_e32 v14, 56, v0
	s_nop 0
	v_cndmask_b32_e32 v76, v198, v76, vcc
	v_cmp_le_i32_e32 vcc, v14, v152
	v_add_u32_e32 v14, 25, v0
	s_nop 0
	v_cndmask_b32_e32 v60, v198, v60, vcc
	v_cmp_le_i32_e32 vcc, v14, v152
	v_add_u32_e32 v14, 57, v0
	s_nop 0
	v_cndmask_b32_e32 v77, v198, v77, vcc
	v_cmp_le_i32_e32 vcc, v14, v152
	v_add_u32_e32 v14, 26, v0
	s_nop 0
	v_cndmask_b32_e32 v61, v198, v61, vcc
	v_cmp_le_i32_e32 vcc, v14, v152
	v_add_u32_e32 v14, 58, v0
	s_nop 0
	v_cndmask_b32_e32 v78, v198, v78, vcc
	v_cmp_le_i32_e32 vcc, v14, v152
	v_add_u32_e32 v14, 27, v0
	v_add_u32_e32 v0, 59, v0
	v_cndmask_b32_e32 v62, v198, v62, vcc
	v_cmp_le_i32_e32 vcc, v14, v152
	s_nop 1
	v_cndmask_b32_e32 v79, v198, v79, vcc
	v_cmp_le_i32_e32 vcc, v0, v152
	s_nop 1
	v_cndmask_b32_e32 v63, v198, v63, vcc
